# v54 + P6 LN-epilogue pass 2 rewritten in regular form: normalise in place, the two 64-byte halves of every 128-byte output line stored back to back
# speedup vs baseline: 1.0238x; 1.0086x over previous
;     __device__ __forceinline__ void fused(f32x4 (&acc)[2][2][4][2], const Unit& u, int wr, int wc, int fr, int fq, PG8_LAS unsigned char* lds, int wid, int lane) const {
;     ...
;         for (int bj = 0; bj < 2; ++bj)
; #pragma unroll
;             for (int n = 0; n < 2; ++n) { const int c = col0 + bj * 128 + n * 16; const f32x4 g4 = *(const f32x4*)(lng + c), b4 = *(const f32x4*)(lnb + c);
; #pragma unroll
;                 for (int ai = 0; ai < 2; ++ai)
; #pragma unroll
;                     for (int m = 0; m < 4; ++m) { const int r = ai * 128 + wr * 64 + m * 16 + fr; const f32x2v sr = S[r];
;                         f32x4 o = (acc[ai][bj][m][n] - sr.x) * sr.y * g4 + b4; if (bad) o = (f32x4){qnan, qnan, qnan, qnan};
;                         *(f32x4*)(out + (size_t)(u.pm * 256 + r) * D + c) = o; }
.LBB0_481:
	s_or_b64 exec, exec, s[4:5]
	v_readlane_b32 s40, v250, 0
	v_readlane_b32 s46, v250, 6
	v_readlane_b32 s47, v250, 7
	v_lshl_add_u64 v[138:139], s[92:93], 0, v[154:155]
	v_lshl_add_u64 v[136:137], s[46:47], 0, v[154:155]
	global_load_dwordx4 v[216:219], v[136:137], off
	global_load_dwordx4 v[232:235], v[138:139], off
	global_load_dwordx4 v[220:223], v[136:137], off offset:64
	global_load_dwordx4 v[236:239], v[138:139], off offset:64
	global_load_dwordx4 v[224:227], v[136:137], off offset:512
	global_load_dwordx4 v[240:243], v[138:139], off offset:512
	global_load_dwordx4 v[228:231], v[136:137], off offset:576
	global_load_dwordx4 v[244:247], v[138:139], off offset:576
	v_lshl_add_u32 v141, v153, 3, 0
	v_add_u32_e32 v148, 0x2000, v141
	v_mov_b32_e32 v192, v152
	v_ashrrev_i32_e32 v193, 31, v192
	v_lshlrev_b64 v[192:193], 12, v[192:193]
	v_lshl_add_u64 v[192:193], s[94:95], 0, v[192:193]
	v_lshl_add_u64 v[192:193], v[192:193], 0, v[154:155]
	v_add_u32_e32 v194, 16, v152
	v_ashrrev_i32_e32 v195, 31, v194
	v_lshlrev_b64 v[194:195], 12, v[194:195]
	v_lshl_add_u64 v[194:195], s[94:95], 0, v[194:195]
	v_lshl_add_u64 v[194:195], v[194:195], 0, v[154:155]
	v_add_u32_e32 v196, 32, v152
	v_ashrrev_i32_e32 v197, 31, v196
	v_lshlrev_b64 v[196:197], 12, v[196:197]
	v_lshl_add_u64 v[196:197], s[94:95], 0, v[196:197]
	v_lshl_add_u64 v[196:197], v[196:197], 0, v[154:155]
	v_add_u32_e32 v198, 48, v152
	v_ashrrev_i32_e32 v199, 31, v198
	v_lshlrev_b64 v[198:199], 12, v[198:199]
	v_lshl_add_u64 v[198:199], s[94:95], 0, v[198:199]
	v_lshl_add_u64 v[198:199], v[198:199], 0, v[154:155]
	v_add_u32_e32 v200, 0x80, v152
	v_ashrrev_i32_e32 v201, 31, v200
	v_lshlrev_b64 v[200:201], 12, v[200:201]
	v_lshl_add_u64 v[200:201], s[94:95], 0, v[200:201]
	v_lshl_add_u64 v[200:201], v[200:201], 0, v[154:155]
	v_add_u32_e32 v202, 0x90, v152
	v_ashrrev_i32_e32 v203, 31, v202
	v_lshlrev_b64 v[202:203], 12, v[202:203]
	v_lshl_add_u64 v[202:203], s[94:95], 0, v[202:203]
	v_lshl_add_u64 v[202:203], v[202:203], 0, v[154:155]
	v_add_u32_e32 v204, 0xa0, v152
	v_ashrrev_i32_e32 v205, 31, v204
	v_lshlrev_b64 v[204:205], 12, v[204:205]
	v_lshl_add_u64 v[204:205], s[94:95], 0, v[204:205]
	v_lshl_add_u64 v[204:205], v[204:205], 0, v[154:155]
	v_add_u32_e32 v206, 0xb0, v152
	v_ashrrev_i32_e32 v207, 31, v206
	v_lshlrev_b64 v[206:207], 12, v[206:207]
	v_lshl_add_u64 v[206:207], s[94:95], 0, v[206:207]
	v_lshl_add_u64 v[206:207], v[206:207], 0, v[154:155]
	v_readlane_b32 s41, v250, 1
	v_readlane_b32 s42, v250, 2
	v_readlane_b32 s43, v250, 3
	v_readlane_b32 s44, v250, 4
	v_readlane_b32 s45, v250, 5
	s_waitcnt lgkmcnt(0)
	s_barrier
	v_cmp_eq_u32_e32 vcc, 0, v160
	ds_read2_b64 v[176:179], v148 offset1:16
	ds_read2_b64 v[180:183], v148 offset0:32 offset1:48
	ds_read2_b64 v[184:187], v148 offset0:128 offset1:144
	ds_read2_b64 v[188:191], v148 offset0:160 offset1:176
	s_waitcnt lgkmcnt(0)
	s_waitcnt vmcnt(4)
	v_sub_f32_e32 v80, v80, v176
	v_sub_f32_e32 v81, v81, v176
	v_sub_f32_e32 v82, v82, v176
	v_sub_f32_e32 v83, v83, v176
	v_pk_mul_f32 v[80:81], v[176:177], v[80:81] op_sel:[1,0]
	v_pk_mul_f32 v[82:83], v[176:177], v[82:83] op_sel:[1,0]
	v_pk_fma_f32 v[80:81], v[216:217], v[80:81], v[232:233]
	v_pk_fma_f32 v[82:83], v[218:219], v[82:83], v[234:235]
	v_cndmask_b32_e32 v80, v173, v80, vcc
	v_cndmask_b32_e32 v81, v173, v81, vcc
	v_cndmask_b32_e32 v82, v173, v82, vcc
	v_cndmask_b32_e32 v83, v173, v83, vcc
	global_store_dwordx4 v[192:193], v[80:83], off
	v_sub_f32_e32 v84, v84, v176
	v_sub_f32_e32 v85, v85, v176
	v_sub_f32_e32 v86, v86, v176
	v_sub_f32_e32 v87, v87, v176
	v_pk_mul_f32 v[84:85], v[176:177], v[84:85] op_sel:[1,0]
	v_pk_mul_f32 v[86:87], v[176:177], v[86:87] op_sel:[1,0]
	v_pk_fma_f32 v[84:85], v[220:221], v[84:85], v[236:237]
	v_pk_fma_f32 v[86:87], v[222:223], v[86:87], v[238:239]
	v_cndmask_b32_e32 v84, v173, v84, vcc
	v_cndmask_b32_e32 v85, v173, v85, vcc
	v_cndmask_b32_e32 v86, v173, v86, vcc
	v_cndmask_b32_e32 v87, v173, v87, vcc
	global_store_dwordx4 v[192:193], v[84:87], off offset:64
	v_sub_f32_e32 v76, v76, v178
	v_sub_f32_e32 v77, v77, v178
	v_sub_f32_e32 v78, v78, v178
	v_sub_f32_e32 v79, v79, v178
	v_pk_mul_f32 v[76:77], v[178:179], v[76:77] op_sel:[1,0]
	v_pk_mul_f32 v[78:79], v[178:179], v[78:79] op_sel:[1,0]
	v_pk_fma_f32 v[76:77], v[216:217], v[76:77], v[232:233]
	v_pk_fma_f32 v[78:79], v[218:219], v[78:79], v[234:235]
	v_cndmask_b32_e32 v76, v173, v76, vcc
	v_cndmask_b32_e32 v77, v173, v77, vcc
	v_cndmask_b32_e32 v78, v173, v78, vcc
	v_cndmask_b32_e32 v79, v173, v79, vcc
	global_store_dwordx4 v[194:195], v[76:79], off
	v_sub_f32_e32 v52, v52, v178
	v_sub_f32_e32 v53, v53, v178
	v_sub_f32_e32 v54, v54, v178
	v_sub_f32_e32 v55, v55, v178
	v_pk_mul_f32 v[52:53], v[178:179], v[52:53] op_sel:[1,0]
	v_pk_mul_f32 v[54:55], v[178:179], v[54:55] op_sel:[1,0]
	v_pk_fma_f32 v[52:53], v[220:221], v[52:53], v[236:237]
	v_pk_fma_f32 v[54:55], v[222:223], v[54:55], v[238:239]
	v_cndmask_b32_e32 v52, v173, v52, vcc
	v_cndmask_b32_e32 v53, v173, v53, vcc
	v_cndmask_b32_e32 v54, v173, v54, vcc
	v_cndmask_b32_e32 v55, v173, v55, vcc
	global_store_dwordx4 v[194:195], v[52:55], off offset:64
	v_sub_f32_e32 v60, v60, v180
	v_sub_f32_e32 v61, v61, v180
	v_sub_f32_e32 v62, v62, v180
	v_sub_f32_e32 v63, v63, v180
	v_pk_mul_f32 v[60:61], v[180:181], v[60:61] op_sel:[1,0]
	v_pk_mul_f32 v[62:63], v[180:181], v[62:63] op_sel:[1,0]
	v_pk_fma_f32 v[60:61], v[216:217], v[60:61], v[232:233]
	v_pk_fma_f32 v[62:63], v[218:219], v[62:63], v[234:235]
	v_cndmask_b32_e32 v60, v173, v60, vcc
	v_cndmask_b32_e32 v61, v173, v61, vcc
	v_cndmask_b32_e32 v62, v173, v62, vcc
	v_cndmask_b32_e32 v63, v173, v63, vcc
;     __device__ __forceinline__ void fused(f32x4 (&acc)[2][2][4][2], const Unit& u, int wr, int wc, int fr, int fq, PG8_LAS unsigned char* lds, int wid, int lane) const {
;     ...
;         for (int bj = 0; bj < 2; ++bj)
; #pragma unroll
;             for (int n = 0; n < 2; ++n) { const int c = col0 + bj * 128 + n * 16; const f32x4 g4 = *(const f32x4*)(lng + c), b4 = *(const f32x4*)(lnb + c);
; #pragma unroll
;                 for (int ai = 0; ai < 2; ++ai)
; #pragma unroll
;                     for (int m = 0; m < 4; ++m) { const int r = ai * 128 + wr * 64 + m * 16 + fr; const f32x2v sr = S[r];
;                         f32x4 o = (acc[ai][bj][m][n] - sr.x) * sr.y * g4 + b4; if (bad) o = (f32x4){qnan, qnan, qnan, qnan};
;                         *(f32x4*)(out + (size_t)(u.pm * 256 + r) * D + c) = o; }
	global_store_dwordx4 v[196:197], v[60:63], off
	v_sub_f32_e32 v32, v32, v180
	v_sub_f32_e32 v33, v33, v180
	v_sub_f32_e32 v34, v34, v180
	v_sub_f32_e32 v35, v35, v180
	v_pk_mul_f32 v[32:33], v[180:181], v[32:33] op_sel:[1,0]
	v_pk_mul_f32 v[34:35], v[180:181], v[34:35] op_sel:[1,0]
	v_pk_fma_f32 v[32:33], v[220:221], v[32:33], v[236:237]
	v_pk_fma_f32 v[34:35], v[222:223], v[34:35], v[238:239]
	v_cndmask_b32_e32 v32, v173, v32, vcc
	v_cndmask_b32_e32 v33, v173, v33, vcc
	v_cndmask_b32_e32 v34, v173, v34, vcc
	v_cndmask_b32_e32 v35, v173, v35, vcc
	global_store_dwordx4 v[196:197], v[32:35], off offset:64
	v_sub_f32_e32 v64, v64, v182
	v_sub_f32_e32 v65, v65, v182
	v_sub_f32_e32 v66, v66, v182
	v_sub_f32_e32 v67, v67, v182
	v_pk_mul_f32 v[64:65], v[182:183], v[64:65] op_sel:[1,0]
	v_pk_mul_f32 v[66:67], v[182:183], v[66:67] op_sel:[1,0]
	v_pk_fma_f32 v[64:65], v[216:217], v[64:65], v[232:233]
	v_pk_fma_f32 v[66:67], v[218:219], v[66:67], v[234:235]
	v_cndmask_b32_e32 v64, v173, v64, vcc
	v_cndmask_b32_e32 v65, v173, v65, vcc
	v_cndmask_b32_e32 v66, v173, v66, vcc
	v_cndmask_b32_e32 v67, v173, v67, vcc
	global_store_dwordx4 v[198:199], v[64:67], off
	v_sub_f32_e32 v16, v16, v182
	v_sub_f32_e32 v17, v17, v182
	v_sub_f32_e32 v18, v18, v182
	v_sub_f32_e32 v19, v19, v182
	v_pk_mul_f32 v[16:17], v[182:183], v[16:17] op_sel:[1,0]
	v_pk_mul_f32 v[18:19], v[182:183], v[18:19] op_sel:[1,0]
	v_pk_fma_f32 v[16:17], v[220:221], v[16:17], v[236:237]
	v_pk_fma_f32 v[18:19], v[222:223], v[18:19], v[238:239]
	v_cndmask_b32_e32 v16, v173, v16, vcc
	v_cndmask_b32_e32 v17, v173, v17, vcc
	v_cndmask_b32_e32 v18, v173, v18, vcc
	v_cndmask_b32_e32 v19, v173, v19, vcc
	global_store_dwordx4 v[198:199], v[16:19], off offset:64
	v_sub_f32_e32 v92, v92, v184
	v_sub_f32_e32 v93, v93, v184
	v_sub_f32_e32 v94, v94, v184
	v_sub_f32_e32 v95, v95, v184
	v_pk_mul_f32 v[92:93], v[184:185], v[92:93] op_sel:[1,0]
	v_pk_mul_f32 v[94:95], v[184:185], v[94:95] op_sel:[1,0]
	v_pk_fma_f32 v[92:93], v[216:217], v[92:93], v[232:233]
	v_pk_fma_f32 v[94:95], v[218:219], v[94:95], v[234:235]
	v_cndmask_b32_e32 v92, v173, v92, vcc
	v_cndmask_b32_e32 v93, v173, v93, vcc
	v_cndmask_b32_e32 v94, v173, v94, vcc
	v_cndmask_b32_e32 v95, v173, v95, vcc
	global_store_dwordx4 v[200:201], v[92:95], off
	v_sub_f32_e32 v68, v68, v184
	v_sub_f32_e32 v69, v69, v184
	v_sub_f32_e32 v70, v70, v184
	v_sub_f32_e32 v71, v71, v184
	v_pk_mul_f32 v[68:69], v[184:185], v[68:69] op_sel:[1,0]
	v_pk_mul_f32 v[70:71], v[184:185], v[70:71] op_sel:[1,0]
	v_pk_fma_f32 v[68:69], v[220:221], v[68:69], v[236:237]
	v_pk_fma_f32 v[70:71], v[222:223], v[70:71], v[238:239]
	v_cndmask_b32_e32 v68, v173, v68, vcc
	v_cndmask_b32_e32 v69, v173, v69, vcc
	v_cndmask_b32_e32 v70, v173, v70, vcc
	v_cndmask_b32_e32 v71, v173, v71, vcc
	global_store_dwordx4 v[200:201], v[68:71], off offset:64
	v_sub_f32_e32 v88, v88, v186
	v_sub_f32_e32 v89, v89, v186
	v_sub_f32_e32 v90, v90, v186
	v_sub_f32_e32 v91, v91, v186
	v_pk_mul_f32 v[88:89], v[186:187], v[88:89] op_sel:[1,0]
	v_pk_mul_f32 v[90:91], v[186:187], v[90:91] op_sel:[1,0]
	v_pk_fma_f32 v[88:89], v[216:217], v[88:89], v[232:233]
	v_pk_fma_f32 v[90:91], v[218:219], v[90:91], v[234:235]
	v_cndmask_b32_e32 v88, v173, v88, vcc
	v_cndmask_b32_e32 v89, v173, v89, vcc
	v_cndmask_b32_e32 v90, v173, v90, vcc
	v_cndmask_b32_e32 v91, v173, v91, vcc
	global_store_dwordx4 v[202:203], v[88:91], off
	v_sub_f32_e32 v48, v48, v186
	v_sub_f32_e32 v49, v49, v186
	v_sub_f32_e32 v50, v50, v186
	v_sub_f32_e32 v51, v51, v186
	v_pk_mul_f32 v[48:49], v[186:187], v[48:49] op_sel:[1,0]
	v_pk_mul_f32 v[50:51], v[186:187], v[50:51] op_sel:[1,0]
	v_pk_fma_f32 v[48:49], v[220:221], v[48:49], v[236:237]
	v_pk_fma_f32 v[50:51], v[222:223], v[50:51], v[238:239]
	v_cndmask_b32_e32 v48, v173, v48, vcc
	v_cndmask_b32_e32 v49, v173, v49, vcc
	v_cndmask_b32_e32 v50, v173, v50, vcc
	v_cndmask_b32_e32 v51, v173, v51, vcc
	global_store_dwordx4 v[202:203], v[48:51], off offset:64
	v_sub_f32_e32 v44, v44, v188
	v_sub_f32_e32 v45, v45, v188
	v_sub_f32_e32 v46, v46, v188
	v_sub_f32_e32 v47, v47, v188
	v_pk_mul_f32 v[44:45], v[188:189], v[44:45] op_sel:[1,0]
	v_pk_mul_f32 v[46:47], v[188:189], v[46:47] op_sel:[1,0]
	v_pk_fma_f32 v[44:45], v[216:217], v[44:45], v[232:233]
	v_pk_fma_f32 v[46:47], v[218:219], v[46:47], v[234:235]
	v_cndmask_b32_e32 v44, v173, v44, vcc
	v_cndmask_b32_e32 v45, v173, v45, vcc
	v_cndmask_b32_e32 v46, v173, v46, vcc
	v_cndmask_b32_e32 v47, v173, v47, vcc
	global_store_dwordx4 v[204:205], v[44:47], off
	v_sub_f32_e32 v24, v24, v188
	v_sub_f32_e32 v25, v25, v188
	v_sub_f32_e32 v26, v26, v188
	v_sub_f32_e32 v27, v27, v188
	v_pk_mul_f32 v[24:25], v[188:189], v[24:25] op_sel:[1,0]
	v_pk_mul_f32 v[26:27], v[188:189], v[26:27] op_sel:[1,0]
	v_pk_fma_f32 v[24:25], v[220:221], v[24:25], v[236:237]
	v_pk_fma_f32 v[26:27], v[222:223], v[26:27], v[238:239]
	v_cndmask_b32_e32 v24, v173, v24, vcc
	v_cndmask_b32_e32 v25, v173, v25, vcc
	v_cndmask_b32_e32 v26, v173, v26, vcc
	v_cndmask_b32_e32 v27, v173, v27, vcc
	global_store_dwordx4 v[204:205], v[24:27], off offset:64
	v_sub_f32_e32 v28, v28, v190
	v_sub_f32_e32 v29, v29, v190
	v_sub_f32_e32 v30, v30, v190
	v_sub_f32_e32 v31, v31, v190
	v_pk_mul_f32 v[28:29], v[190:191], v[28:29] op_sel:[1,0]
	v_pk_mul_f32 v[30:31], v[190:191], v[30:31] op_sel:[1,0]
	v_pk_fma_f32 v[28:29], v[216:217], v[28:29], v[232:233]
	v_pk_fma_f32 v[30:31], v[218:219], v[30:31], v[234:235]
	v_cndmask_b32_e32 v28, v173, v28, vcc
	v_cndmask_b32_e32 v29, v173, v29, vcc
	v_cndmask_b32_e32 v30, v173, v30, vcc
	v_cndmask_b32_e32 v31, v173, v31, vcc
	global_store_dwordx4 v[206:207], v[28:31], off
	v_sub_f32_e32 v8, v8, v190
	v_sub_f32_e32 v9, v9, v190
	v_sub_f32_e32 v10, v10, v190
	v_sub_f32_e32 v11, v11, v190
	v_pk_mul_f32 v[8:9], v[190:191], v[8:9] op_sel:[1,0]
	v_pk_mul_f32 v[10:11], v[190:191], v[10:11] op_sel:[1,0]
	v_pk_fma_f32 v[8:9], v[220:221], v[8:9], v[236:237]
	v_pk_fma_f32 v[10:11], v[222:223], v[10:11], v[238:239]
	v_cndmask_b32_e32 v8, v173, v8, vcc
	v_cndmask_b32_e32 v9, v173, v9, vcc
	v_cndmask_b32_e32 v10, v173, v10, vcc
	v_cndmask_b32_e32 v11, v173, v11, vcc
	global_store_dwordx4 v[206:207], v[8:11], off offset:64
	s_waitcnt vmcnt(16)
;     __device__ __forceinline__ void fused(f32x4 (&acc)[2][2][4][2], const Unit& u, int wr, int wc, int fr, int fq, PG8_LAS unsigned char* lds, int wid, int lane) const {
;     ...
;         for (int bj = 0; bj < 2; ++bj)
; #pragma unroll
;             for (int n = 0; n < 2; ++n) { const int c = col0 + bj * 128 + n * 16; const f32x4 g4 = *(const f32x4*)(lng + c), b4 = *(const f32x4*)(lnb + c);
; #pragma unroll
;                 for (int ai = 0; ai < 2; ++ai)
; #pragma unroll
;                     for (int m = 0; m < 4; ++m) { const int r = ai * 128 + wr * 64 + m * 16 + fr; const f32x2v sr = S[r];
;                         f32x4 o = (acc[ai][bj][m][n] - sr.x) * sr.y * g4 + b4; if (bad) o = (f32x4){qnan, qnan, qnan, qnan};
;                         *(f32x4*)(out + (size_t)(u.pm * 256 + r) * D + c) = o; }
	v_sub_f32_e32 v72, v72, v176
	v_sub_f32_e32 v73, v73, v176
	v_sub_f32_e32 v74, v74, v176
	v_sub_f32_e32 v75, v75, v176
	v_pk_mul_f32 v[72:73], v[176:177], v[72:73] op_sel:[1,0]
	v_pk_mul_f32 v[74:75], v[176:177], v[74:75] op_sel:[1,0]
	v_pk_fma_f32 v[72:73], v[224:225], v[72:73], v[240:241]
	v_pk_fma_f32 v[74:75], v[226:227], v[74:75], v[242:243]
	v_cndmask_b32_e32 v72, v173, v72, vcc
	v_cndmask_b32_e32 v73, v173, v73, vcc
	v_cndmask_b32_e32 v74, v173, v74, vcc
	v_cndmask_b32_e32 v75, v173, v75, vcc
	global_store_dwordx4 v[192:193], v[72:75], off offset:512
	v_sub_f32_e32 v116, v116, v176
	v_sub_f32_e32 v117, v117, v176
	v_sub_f32_e32 v118, v118, v176
	v_sub_f32_e32 v119, v119, v176
	v_pk_mul_f32 v[116:117], v[176:177], v[116:117] op_sel:[1,0]
	v_pk_mul_f32 v[118:119], v[176:177], v[118:119] op_sel:[1,0]
	v_pk_fma_f32 v[116:117], v[228:229], v[116:117], v[244:245]
	v_pk_fma_f32 v[118:119], v[230:231], v[118:119], v[246:247]
	v_cndmask_b32_e32 v116, v173, v116, vcc
	v_cndmask_b32_e32 v117, v173, v117, vcc
	v_cndmask_b32_e32 v118, v173, v118, vcc
	v_cndmask_b32_e32 v119, v173, v119, vcc
	global_store_dwordx4 v[192:193], v[116:119], off offset:576
	v_sub_f32_e32 v40, v40, v178
	v_sub_f32_e32 v41, v41, v178
	v_sub_f32_e32 v42, v42, v178
	v_sub_f32_e32 v43, v43, v178
	v_pk_mul_f32 v[40:41], v[178:179], v[40:41] op_sel:[1,0]
	v_pk_mul_f32 v[42:43], v[178:179], v[42:43] op_sel:[1,0]
	v_pk_fma_f32 v[40:41], v[224:225], v[40:41], v[240:241]
	v_pk_fma_f32 v[42:43], v[226:227], v[42:43], v[242:243]
	v_cndmask_b32_e32 v40, v173, v40, vcc
	v_cndmask_b32_e32 v41, v173, v41, vcc
	v_cndmask_b32_e32 v42, v173, v42, vcc
	v_cndmask_b32_e32 v43, v173, v43, vcc
	global_store_dwordx4 v[194:195], v[40:43], off offset:512
	v_sub_f32_e32 v108, v108, v178
	v_sub_f32_e32 v109, v109, v178
	v_sub_f32_e32 v110, v110, v178
	v_sub_f32_e32 v111, v111, v178
	v_pk_mul_f32 v[108:109], v[178:179], v[108:109] op_sel:[1,0]
	v_pk_mul_f32 v[110:111], v[178:179], v[110:111] op_sel:[1,0]
	v_pk_fma_f32 v[108:109], v[228:229], v[108:109], v[244:245]
	v_pk_fma_f32 v[110:111], v[230:231], v[110:111], v[246:247]
	v_cndmask_b32_e32 v108, v173, v108, vcc
	v_cndmask_b32_e32 v109, v173, v109, vcc
	v_cndmask_b32_e32 v110, v173, v110, vcc
	v_cndmask_b32_e32 v111, v173, v111, vcc
	global_store_dwordx4 v[194:195], v[108:111], off offset:576
	v_sub_f32_e32 v20, v20, v180
	v_sub_f32_e32 v21, v21, v180
	v_sub_f32_e32 v22, v22, v180
	v_sub_f32_e32 v23, v23, v180
	v_pk_mul_f32 v[20:21], v[180:181], v[20:21] op_sel:[1,0]
	v_pk_mul_f32 v[22:23], v[180:181], v[22:23] op_sel:[1,0]
	v_pk_fma_f32 v[20:21], v[224:225], v[20:21], v[240:241]
	v_pk_fma_f32 v[22:23], v[226:227], v[22:23], v[242:243]
	v_cndmask_b32_e32 v20, v173, v20, vcc
	v_cndmask_b32_e32 v21, v173, v21, vcc
	v_cndmask_b32_e32 v22, v173, v22, vcc
	v_cndmask_b32_e32 v23, v173, v23, vcc
	global_store_dwordx4 v[196:197], v[20:23], off offset:512
	v_sub_f32_e32 v100, v100, v180
	v_sub_f32_e32 v101, v101, v180
	v_sub_f32_e32 v102, v102, v180
	v_sub_f32_e32 v103, v103, v180
	v_pk_mul_f32 v[100:101], v[180:181], v[100:101] op_sel:[1,0]
	v_pk_mul_f32 v[102:103], v[180:181], v[102:103] op_sel:[1,0]
	v_pk_fma_f32 v[100:101], v[228:229], v[100:101], v[244:245]
	v_pk_fma_f32 v[102:103], v[230:231], v[102:103], v[246:247]
	v_cndmask_b32_e32 v100, v173, v100, vcc
	v_cndmask_b32_e32 v101, v173, v101, vcc
	v_cndmask_b32_e32 v102, v173, v102, vcc
	v_cndmask_b32_e32 v103, v173, v103, vcc
	global_store_dwordx4 v[196:197], v[100:103], off offset:576
	v_sub_f32_e32 v4, v4, v182
	v_sub_f32_e32 v5, v5, v182
	v_sub_f32_e32 v6, v6, v182
	v_sub_f32_e32 v7, v7, v182
	v_pk_mul_f32 v[4:5], v[182:183], v[4:5] op_sel:[1,0]
	v_pk_mul_f32 v[6:7], v[182:183], v[6:7] op_sel:[1,0]
	v_pk_fma_f32 v[4:5], v[224:225], v[4:5], v[240:241]
	v_pk_fma_f32 v[6:7], v[226:227], v[6:7], v[242:243]
	v_cndmask_b32_e32 v4, v173, v4, vcc
	v_cndmask_b32_e32 v5, v173, v5, vcc
	v_cndmask_b32_e32 v6, v173, v6, vcc
	v_cndmask_b32_e32 v7, v173, v7, vcc
	global_store_dwordx4 v[198:199], v[4:7], off offset:512
	v_sub_f32_e32 v96, v96, v182
	v_sub_f32_e32 v97, v97, v182
	v_sub_f32_e32 v98, v98, v182
	v_sub_f32_e32 v99, v99, v182
	v_pk_mul_f32 v[96:97], v[182:183], v[96:97] op_sel:[1,0]
	v_pk_mul_f32 v[98:99], v[182:183], v[98:99] op_sel:[1,0]
	v_pk_fma_f32 v[96:97], v[228:229], v[96:97], v[244:245]
	v_pk_fma_f32 v[98:99], v[230:231], v[98:99], v[246:247]
	v_cndmask_b32_e32 v96, v173, v96, vcc
	v_cndmask_b32_e32 v97, v173, v97, vcc
	v_cndmask_b32_e32 v98, v173, v98, vcc
	v_cndmask_b32_e32 v99, v173, v99, vcc
	global_store_dwordx4 v[198:199], v[96:99], off offset:576
	v_sub_f32_e32 v56, v56, v184
;     __device__ __forceinline__ void fused(f32x4 (&acc)[2][2][4][2], const Unit& u, int wr, int wc, int fr, int fq, PG8_LAS unsigned char* lds, int wid, int lane) const {
;     ...
;         for (int bj = 0; bj < 2; ++bj)
; #pragma unroll
;             for (int n = 0; n < 2; ++n) { const int c = col0 + bj * 128 + n * 16; const f32x4 g4 = *(const f32x4*)(lng + c), b4 = *(const f32x4*)(lnb + c);
; #pragma unroll
;                 for (int ai = 0; ai < 2; ++ai)
; #pragma unroll
;                     for (int m = 0; m < 4; ++m) { const int r = ai * 128 + wr * 64 + m * 16 + fr; const f32x2v sr = S[r];
;                         f32x4 o = (acc[ai][bj][m][n] - sr.x) * sr.y * g4 + b4; if (bad) o = (f32x4){qnan, qnan, qnan, qnan};
;                         *(f32x4*)(out + (size_t)(u.pm * 256 + r) * D + c) = o; }
	v_sub_f32_e32 v57, v57, v184
	v_sub_f32_e32 v58, v58, v184
	v_sub_f32_e32 v59, v59, v184
	v_pk_mul_f32 v[56:57], v[184:185], v[56:57] op_sel:[1,0]
	v_pk_mul_f32 v[58:59], v[184:185], v[58:59] op_sel:[1,0]
	v_pk_fma_f32 v[56:57], v[224:225], v[56:57], v[240:241]
	v_pk_fma_f32 v[58:59], v[226:227], v[58:59], v[242:243]
	v_cndmask_b32_e32 v56, v173, v56, vcc
	v_cndmask_b32_e32 v57, v173, v57, vcc
	v_cndmask_b32_e32 v58, v173, v58, vcc
	v_cndmask_b32_e32 v59, v173, v59, vcc
	global_store_dwordx4 v[200:201], v[56:59], off offset:512
	v_sub_f32_e32 v124, v124, v184
	v_sub_f32_e32 v125, v125, v184
	v_sub_f32_e32 v126, v126, v184
	v_sub_f32_e32 v127, v127, v184
	v_pk_mul_f32 v[124:125], v[184:185], v[124:125] op_sel:[1,0]
	v_pk_mul_f32 v[126:127], v[184:185], v[126:127] op_sel:[1,0]
	v_pk_fma_f32 v[124:125], v[228:229], v[124:125], v[244:245]
	v_pk_fma_f32 v[126:127], v[230:231], v[126:127], v[246:247]
	v_cndmask_b32_e32 v124, v173, v124, vcc
	v_cndmask_b32_e32 v125, v173, v125, vcc
	v_cndmask_b32_e32 v126, v173, v126, vcc
	v_cndmask_b32_e32 v127, v173, v127, vcc
	global_store_dwordx4 v[200:201], v[124:127], off offset:576
	v_sub_f32_e32 v36, v36, v186
	v_sub_f32_e32 v37, v37, v186
	v_sub_f32_e32 v38, v38, v186
	v_sub_f32_e32 v39, v39, v186
	v_pk_mul_f32 v[36:37], v[186:187], v[36:37] op_sel:[1,0]
	v_pk_mul_f32 v[38:39], v[186:187], v[38:39] op_sel:[1,0]
	v_pk_fma_f32 v[36:37], v[224:225], v[36:37], v[240:241]
	v_pk_fma_f32 v[38:39], v[226:227], v[38:39], v[242:243]
	v_cndmask_b32_e32 v36, v173, v36, vcc
	v_cndmask_b32_e32 v37, v173, v37, vcc
	v_cndmask_b32_e32 v38, v173, v38, vcc
	v_cndmask_b32_e32 v39, v173, v39, vcc
	global_store_dwordx4 v[202:203], v[36:39], off offset:512
	v_sub_f32_e32 v120, v120, v186
	v_sub_f32_e32 v121, v121, v186
	v_sub_f32_e32 v122, v122, v186
	v_sub_f32_e32 v123, v123, v186
	v_pk_mul_f32 v[120:121], v[186:187], v[120:121] op_sel:[1,0]
	v_pk_mul_f32 v[122:123], v[186:187], v[122:123] op_sel:[1,0]
	v_pk_fma_f32 v[120:121], v[228:229], v[120:121], v[244:245]
	v_pk_fma_f32 v[122:123], v[230:231], v[122:123], v[246:247]
	v_cndmask_b32_e32 v120, v173, v120, vcc
	v_cndmask_b32_e32 v121, v173, v121, vcc
	v_cndmask_b32_e32 v122, v173, v122, vcc
	v_cndmask_b32_e32 v123, v173, v123, vcc
	global_store_dwordx4 v[202:203], v[120:123], off offset:576
	v_sub_f32_e32 v12, v12, v188
	v_sub_f32_e32 v13, v13, v188
	v_sub_f32_e32 v14, v14, v188
	v_sub_f32_e32 v15, v15, v188
	v_pk_mul_f32 v[12:13], v[188:189], v[12:13] op_sel:[1,0]
	v_pk_mul_f32 v[14:15], v[188:189], v[14:15] op_sel:[1,0]
	v_pk_fma_f32 v[12:13], v[224:225], v[12:13], v[240:241]
	v_pk_fma_f32 v[14:15], v[226:227], v[14:15], v[242:243]
	v_cndmask_b32_e32 v12, v173, v12, vcc
	v_cndmask_b32_e32 v13, v173, v13, vcc
	v_cndmask_b32_e32 v14, v173, v14, vcc
	v_cndmask_b32_e32 v15, v173, v15, vcc
	global_store_dwordx4 v[204:205], v[12:15], off offset:512
	v_sub_f32_e32 v112, v112, v188
	v_sub_f32_e32 v113, v113, v188
	v_sub_f32_e32 v114, v114, v188
	v_sub_f32_e32 v115, v115, v188
	v_pk_mul_f32 v[112:113], v[188:189], v[112:113] op_sel:[1,0]
	v_pk_mul_f32 v[114:115], v[188:189], v[114:115] op_sel:[1,0]
	v_pk_fma_f32 v[112:113], v[228:229], v[112:113], v[244:245]
	v_pk_fma_f32 v[114:115], v[230:231], v[114:115], v[246:247]
	v_cndmask_b32_e32 v112, v173, v112, vcc
	v_cndmask_b32_e32 v113, v173, v113, vcc
	v_cndmask_b32_e32 v114, v173, v114, vcc
	v_cndmask_b32_e32 v115, v173, v115, vcc
	global_store_dwordx4 v[204:205], v[112:115], off offset:576
	v_sub_f32_e32 v0, v0, v190
	v_sub_f32_e32 v1, v1, v190
	v_sub_f32_e32 v2, v2, v190
	v_sub_f32_e32 v3, v3, v190
	v_pk_mul_f32 v[0:1], v[190:191], v[0:1] op_sel:[1,0]
	v_pk_mul_f32 v[2:3], v[190:191], v[2:3] op_sel:[1,0]
	v_pk_fma_f32 v[0:1], v[224:225], v[0:1], v[240:241]
	v_pk_fma_f32 v[2:3], v[226:227], v[2:3], v[242:243]
	v_cndmask_b32_e32 v0, v173, v0, vcc
	v_cndmask_b32_e32 v1, v173, v1, vcc
	v_cndmask_b32_e32 v2, v173, v2, vcc
	v_cndmask_b32_e32 v3, v173, v3, vcc
	global_store_dwordx4 v[206:207], v[0:3], off offset:512
	v_sub_f32_e32 v104, v104, v190
	v_sub_f32_e32 v105, v105, v190
	v_sub_f32_e32 v106, v106, v190
	v_sub_f32_e32 v107, v107, v190
	v_pk_mul_f32 v[104:105], v[190:191], v[104:105] op_sel:[1,0]
	v_pk_mul_f32 v[106:107], v[190:191], v[106:107] op_sel:[1,0]
	v_pk_fma_f32 v[104:105], v[228:229], v[104:105], v[244:245]
	v_pk_fma_f32 v[106:107], v[230:231], v[106:107], v[246:247]
	v_cndmask_b32_e32 v104, v173, v104, vcc
	v_cndmask_b32_e32 v105, v173, v105, vcc
	v_cndmask_b32_e32 v106, v173, v106, vcc
	v_cndmask_b32_e32 v107, v173, v107, vcc
	global_store_dwordx4 v[206:207], v[104:107], off offset:576
